# FoX attention tile loop: K and V fragment LDS reads issued four steps ahead of their MFMAs (rotating buffers)
# speedup vs baseline: 1.0020x; 1.0020x over previous
; #define LAS __attribute__((address_space(3)))
; __device__ __forceinline__ f32x4 mfma16(bf16x8 a, bf16x8 b, f32x4 c) { return __builtin_amdgcn_mfma_f32_16x16x32_bf16(a, b, c, 0, 0, 0); }
; template <bool FOX> ...
;     f32x4 s[2][4];
; #pragma unroll
;     for (int mt = 0; mt < 4; ++mt) {
;         s[0][mt] = (f32x4){0.f, 0.f, 0.f, 0.f}; s[1][mt] = (f32x4){0.f, 0.f, 0.f, 0.f};
; #pragma unroll
;         for (int ks = 0; ks < 4; ++ks) { const bf16x8 kf = *(const LAS bf16x8*)(Ks + (mt * 16 + fr) * 136 + ks * 32 + fq * 8); s[0][mt] = mfma16(kf, qf[0][ks], s[0][mt]); s[1][mt] = mfma16(kf, qf[1][ks], s[1][mt]); }
;     }
;     if (FOX) {
; #pragma unroll
;         for (int mt = 0; mt < 4; ++mt) { const f32x4 ck = *(const LAS f32x4*)(cum + j * 64 + mt * 16 + fq * 4);
; #pragma unroll
;             for (int e = 0; e < 4; ++e) { s[0][mt][e] += cq[0] - ck[e]; s[1][mt][e] += cq[1] - ck[e]; } }
.LBB0_269:
	s_cmp_gt_i32 s2, s3
	s_cbranch_scc1 .LBB0_273
	ds_read_b128 v[234:237], v228
	ds_read_b128 v[246:249], v228 offset:64
	ds_read_b128 v[250:253], v228 offset:128
	ds_read_b128 v[186:189], v228 offset:192
	ds_read_b128 v[194:197], v227
	s_cmp_lt_u32 s42, s28
	s_waitcnt lgkmcnt(4)
	v_mfma_f32_16x16x32_bf16 v[140:143], v[234:237], v[0:3], 0
	s_waitcnt lgkmcnt(0)
	v_sub_f32_e32 v167, v35, v197
	v_sub_f32_e32 v166, v68, v196
	v_mfma_f32_16x16x32_bf16 v[136:139], v[234:237], v[16:19], 0
	ds_read_b128 v[234:237], v228 offset:4352
	v_mfma_f32_16x16x32_bf16 v[140:143], v[246:249], v[4:7], v[140:143]
	v_mfma_f32_16x16x32_bf16 v[136:139], v[246:249], v[20:23], v[136:139]
	ds_read_b128 v[246:249], v228 offset:4416
	v_mfma_f32_16x16x32_bf16 v[140:143], v[250:253], v[8:11], v[140:143]
	v_mfma_f32_16x16x32_bf16 v[136:139], v[250:253], v[24:27], v[136:139]
	ds_read_b128 v[250:253], v228 offset:4480
	v_mfma_f32_16x16x32_bf16 v[190:193], v[186:189], v[28:31], v[136:139]
	s_nop 4
	v_mfma_f32_16x16x32_bf16 v[182:185], v[186:189], v[12:15], v[140:143]
	ds_read_b128 v[186:189], v228 offset:4544
	s_waitcnt lgkmcnt(3)
	v_mfma_f32_16x16x32_bf16 v[140:143], v[234:237], v[0:3], 0
	v_mfma_f32_16x16x32_bf16 v[136:139], v[234:237], v[16:19], 0
	ds_read_b128 v[234:237], v228 offset:8704
	s_waitcnt lgkmcnt(3)
	v_mfma_f32_16x16x32_bf16 v[140:143], v[246:249], v[4:7], v[140:143]
	v_mfma_f32_16x16x32_bf16 v[136:139], v[246:249], v[20:23], v[136:139]
	ds_read_b128 v[246:249], v228 offset:8768
	s_waitcnt lgkmcnt(3)
	v_mfma_f32_16x16x32_bf16 v[140:143], v[250:253], v[8:11], v[140:143]
	v_mfma_f32_16x16x32_bf16 v[136:139], v[250:253], v[24:27], v[136:139]
	ds_read_b128 v[250:253], v228 offset:8832
	s_waitcnt lgkmcnt(3)
	v_mfma_f32_16x16x32_bf16 v[152:155], v[186:189], v[12:15], v[140:143]
	v_mfma_f32_16x16x32_bf16 v[144:147], v[186:189], v[28:31], v[136:139]
	ds_read_b128 v[186:189], v228 offset:8896
	s_nop 3
	s_waitcnt lgkmcnt(3)
	v_mfma_f32_16x16x32_bf16 v[140:143], v[234:237], v[0:3], 0
	v_mfma_f32_16x16x32_bf16 v[136:139], v[234:237], v[16:19], 0
	ds_read_b128 v[234:237], v228 offset:13056
	s_waitcnt lgkmcnt(3)
	v_mfma_f32_16x16x32_bf16 v[140:143], v[246:249], v[4:7], v[140:143]
	v_mfma_f32_16x16x32_bf16 v[136:139], v[246:249], v[20:23], v[136:139]
	ds_read_b128 v[246:249], v228 offset:13120
	s_waitcnt lgkmcnt(3)
	v_mfma_f32_16x16x32_bf16 v[140:143], v[250:253], v[8:11], v[140:143]
	v_mfma_f32_16x16x32_bf16 v[136:139], v[250:253], v[24:27], v[136:139]
	ds_read_b128 v[250:253], v228 offset:13184
	s_waitcnt lgkmcnt(3)
	v_mfma_f32_16x16x32_bf16 v[156:159], v[186:189], v[12:15], v[140:143]
	v_mfma_f32_16x16x32_bf16 v[148:151], v[186:189], v[28:31], v[136:139]
	ds_read_b128 v[186:189], v228 offset:13248
	s_nop 3
	s_waitcnt lgkmcnt(3)
	v_mfma_f32_16x16x32_bf16 v[140:143], v[234:237], v[0:3], 0
	v_mfma_f32_16x16x32_bf16 v[136:139], v[234:237], v[16:19], 0
	s_waitcnt lgkmcnt(2)
	v_mfma_f32_16x16x32_bf16 v[140:143], v[246:249], v[4:7], v[140:143]
	v_mfma_f32_16x16x32_bf16 v[136:139], v[246:249], v[20:23], v[136:139]
	s_waitcnt lgkmcnt(1)
	v_mfma_f32_16x16x32_bf16 v[140:143], v[250:253], v[8:11], v[140:143]
	v_mfma_f32_16x16x32_bf16 v[136:139], v[250:253], v[24:27], v[136:139]
	s_waitcnt lgkmcnt(0)
	v_mfma_f32_16x16x32_bf16 v[140:143], v[186:189], v[12:15], v[140:143]
	v_mfma_f32_16x16x32_bf16 v[136:139], v[186:189], v[28:31], v[136:139]
	v_sub_f32_e32 v187, v33, v195
	v_sub_f32_e32 v186, v32, v194
	v_pk_add_f32 v[188:189], v[182:183], v[186:187]
	v_pk_add_f32 v[186:187], v[184:185], v[166:167]
	v_sub_f32_e32 v167, v71, v197
	v_sub_f32_e32 v166, v70, v196
	v_sub_f32_e32 v183, v69, v195
	v_sub_f32_e32 v182, v34, v194
	ds_read_b128 v[194:197], v227 offset:64
	v_pk_add_f32 v[184:185], v[190:191], v[182:183]
	v_pk_add_f32 v[182:183], v[192:193], v[166:167]
	s_waitcnt lgkmcnt(0)
	v_sub_f32_e32 v167, v35, v197
	v_sub_f32_e32 v166, v68, v196
	v_sub_f32_e32 v191, v33, v195
	v_sub_f32_e32 v190, v32, v194
	v_pk_add_f32 v[190:191], v[152:153], v[190:191]
	v_pk_add_f32 v[192:193], v[154:155], v[166:167]
	v_sub_f32_e32 v153, v71, v197
	v_sub_f32_e32 v152, v70, v196
	v_sub_f32_e32 v155, v69, v195
	v_sub_f32_e32 v154, v34, v194
	v_pk_add_f32 v[154:155], v[144:145], v[154:155]
	v_pk_add_f32 v[152:153], v[146:147], v[152:153]
	ds_read_b128 v[144:147], v227 offset:128
	s_waitcnt lgkmcnt(0)
	v_sub_f32_e32 v195, v33, v145
	v_sub_f32_e32 v194, v32, v144
	v_pk_add_f32 v[196:197], v[156:157], v[194:195]
	v_sub_f32_e32 v157, v71, v147
	v_sub_f32_e32 v156, v70, v146
	v_sub_f32_e32 v145, v69, v145
	v_sub_f32_e32 v144, v34, v144
	v_sub_f32_e32 v167, v35, v147
	v_sub_f32_e32 v166, v68, v146
	v_pk_add_f32 v[146:147], v[148:149], v[144:145]
	v_pk_add_f32 v[144:145], v[150:151], v[156:157]
	ds_read_b128 v[148:151], v227 offset:192
	v_pk_add_f32 v[194:195], v[158:159], v[166:167]
	s_waitcnt lgkmcnt(0)
	v_sub_f32_e32 v157, v35, v151
	v_sub_f32_e32 v156, v68, v150
	v_sub_f32_e32 v159, v33, v149
	v_sub_f32_e32 v158, v32, v148
	v_sub_f32_e32 v151, v71, v151
	v_sub_f32_e32 v150, v70, v150
	v_sub_f32_e32 v149, v69, v149
	v_sub_f32_e32 v148, v34, v148
	v_pk_add_f32 v[140:141], v[140:141], v[158:159]
	v_pk_add_f32 v[142:143], v[142:143], v[156:157]
	v_pk_add_f32 v[148:149], v[136:137], v[148:149]
	v_pk_add_f32 v[150:151], v[138:139], v[150:151]
	s_cbranch_scc1 .LBB0_272
; template <bool FOX> ...
;     ...
;         if (diag) {
; #pragma unroll
;             for (int g = 0; g < 2; ++g)
; #pragma unroll
;                 for (int mt = 0; mt < 4; ++mt)
; #pragma unroll
;                     for (int e = 0; e < 4; ++e) if (j * 64 + mt * 16 + fq * 4 + e > qpos[g]) s[g][mt][e] = -INFINITY;
;         }
;     }
;     bf16x8 pf[2][2];
; #pragma unroll
;     for (int g = 0; g < 2; ++g) {
;         float mx = -INFINITY;
; #pragma unroll
;         for (int mt = 0; mt < 4; ++mt)
; #pragma unroll
;             for (int e = 0; e < 4; ++e) mx = fmaxf(mx, s[g][mt][e]);
;         mx = fmaxf(mx, __shfl_xor(mx, 16)); mx = fmaxf(mx, __shfl_xor(mx, 32));
;         const float m_new = fmaxf(m_run[g], mx);
	v_add_u32_e32 v137, s2, v221
	v_mov_b32_e32 v136, s33
	v_cmp_gt_i32_e32 vcc, v137, v175
	v_cmp_lt_i32_e64 s[4:5], v137, v175
	v_add_u32_e32 v138, 2, v137
	v_cndmask_b32_e32 v136, v188, v136, vcc
	v_cndmask_b32_e64 v188, v136, v188, s[4:5]
	v_cndmask_b32_e64 v189, v243, v189, s[4:5]
	v_cmp_le_i32_e64 s[4:5], v138, v175
	v_add_u32_e32 v139, 3, v137
	v_add_u32_e32 v156, 16, v137
	v_cndmask_b32_e64 v186, v243, v186, s[4:5]
	v_cmp_le_i32_e64 s[4:5], v139, v175
	v_mov_b32_e32 v136, s33
	v_add_u32_e32 v157, 18, v137
	v_cndmask_b32_e64 v187, v243, v187, s[4:5]
	v_cmp_gt_i32_e64 s[4:5], v156, v175
	v_add_u32_e32 v156, 17, v137
	v_add_u32_e32 v158, 19, v137
	v_cndmask_b32_e64 v190, v190, v136, s[4:5]
	v_cmp_le_i32_e64 s[4:5], v156, v175
	v_add_u32_e32 v159, 32, v137
	v_add_u32_e32 v160, 33, v137
	v_cndmask_b32_e64 v191, v243, v191, s[4:5]
	v_cmp_le_i32_e64 s[4:5], v157, v175
	v_add_u32_e32 v166, 34, v137
	v_add_u32_e32 v167, 35, v137
	v_cndmask_b32_e64 v192, v243, v192, s[4:5]
	v_cmp_le_i32_e64 s[4:5], v158, v175
	v_add_u32_e32 v200, 48, v137
	v_add_u32_e32 v201, 49, v137
	v_cndmask_b32_e64 v193, v243, v193, s[4:5]
	v_cmp_gt_i32_e64 s[4:5], v159, v175
	v_add_u32_e32 v202, 50, v137
	v_add_u32_e32 v203, 51, v137
	v_cndmask_b32_e64 v196, v196, v136, s[4:5]
	v_cmp_le_i32_e64 s[4:5], v160, v175
	s_nop 1
	v_cndmask_b32_e64 v197, v243, v197, s[4:5]
	v_cmp_le_i32_e64 s[4:5], v166, v175
	s_nop 1
	v_cndmask_b32_e64 v194, v243, v194, s[4:5]
	v_cmp_le_i32_e64 s[4:5], v167, v175
	s_nop 1
	v_cndmask_b32_e64 v195, v243, v195, s[4:5]
	v_cmp_gt_i32_e64 s[4:5], v200, v175
	s_nop 1
	v_cndmask_b32_e64 v140, v140, v136, s[4:5]
	v_cmp_le_i32_e64 s[4:5], v201, v175
	s_nop 1
	v_cndmask_b32_e64 v141, v243, v141, s[4:5]
	v_cmp_le_i32_e64 s[4:5], v202, v175
	s_nop 1
	v_cndmask_b32_e64 v142, v243, v142, s[4:5]
	v_cmp_le_i32_e64 s[4:5], v203, v175
	s_nop 1
	v_cndmask_b32_e64 v143, v243, v143, s[4:5]
	v_cmp_gt_i32_e64 s[4:5], v137, v179
	s_nop 1
	v_cndmask_b32_e64 v136, v184, v136, s[4:5]
	v_cmp_lt_i32_e64 s[4:5], v137, v179
	s_nop 1
	v_cndmask_b32_e64 v184, v136, v184, s[4:5]
	v_mov_b32_e32 v136, s33
	v_cndmask_b32_e32 v154, v154, v136, vcc
	v_cmp_le_i32_e32 vcc, v156, v179
	v_cndmask_b32_e64 v185, v243, v185, s[4:5]
	v_cmp_le_i32_e64 s[4:5], v138, v179
	v_cndmask_b32_e32 v155, v243, v155, vcc
	v_cmp_le_i32_e32 vcc, v157, v179
	v_cndmask_b32_e64 v182, v243, v182, s[4:5]
	v_cmp_le_i32_e64 s[4:5], v139, v179
	v_cndmask_b32_e32 v152, v243, v152, vcc
	v_cmp_le_i32_e32 vcc, v158, v179
	v_cndmask_b32_e64 v183, v243, v183, s[4:5]
	s_nop 0
	v_cndmask_b32_e32 v153, v243, v153, vcc
	v_cmp_gt_i32_e32 vcc, v159, v179
	s_nop 1
	v_cndmask_b32_e32 v146, v146, v136, vcc
	v_cmp_le_i32_e32 vcc, v160, v179
	s_nop 1
	v_cndmask_b32_e32 v147, v243, v147, vcc
	v_cmp_le_i32_e32 vcc, v166, v179
	s_nop 1
	v_cndmask_b32_e32 v144, v243, v144, vcc
	v_cmp_le_i32_e32 vcc, v167, v179
	s_nop 1
	v_cndmask_b32_e32 v145, v243, v145, vcc
	v_cmp_gt_i32_e32 vcc, v200, v179
	s_nop 1
	v_cndmask_b32_e32 v148, v148, v136, vcc
	v_cmp_le_i32_e32 vcc, v201, v179
	s_nop 1
	v_cndmask_b32_e32 v149, v243, v149, vcc
	v_cmp_le_i32_e32 vcc, v202, v179
	s_nop 1
	v_cndmask_b32_e32 v150, v243, v150, vcc
	v_cmp_le_i32_e32 vcc, v203, v179
	s_nop 1
	v_cndmask_b32_e32 v151, v243, v151, vcc
.LBB0_272:
	v_max3_f32 v136, v188, s33, v189
	v_max3_f32 v136, v136, v186, v187
	v_max3_f32 v156, v184, s33, v185
	v_max3_f32 v136, v136, v190, v191
	v_max3_f32 v156, v156, v182, v183
	v_max3_f32 v136, v136, v192, v193
	v_max3_f32 v156, v156, v154, v155
	v_max3_f32 v136, v136, v196, v197
	v_max3_f32 v156, v156, v152, v153
	v_max3_f32 v136, v136, v194, v195
	v_max3_f32 v156, v156, v146, v147
	v_max3_f32 v136, v136, v140, v141
	v_max3_f32 v156, v156, v144, v145
	v_max3_f32 v136, v136, v142, v143
	v_max3_f32 v156, v156, v148, v149
	ds_bpermute_b32 v137, v216, v136
	v_max3_f32 v156, v156, v150, v151
	ds_bpermute_b32 v158, v216, v156
	s_waitcnt lgkmcnt(1)
	v_max_f32_e32 v137, v137, v137
	v_max_f32_e32 v136, v136, v137
	s_waitcnt lgkmcnt(0)
	v_max_f32_e32 v158, v158, v158
	ds_bpermute_b32 v137, v215, v136
	v_max_f32_e32 v156, v156, v158
	ds_bpermute_b32 v158, v215, v156
	s_waitcnt lgkmcnt(1)
	v_max3_f32 v232, v199, v136, v137
	v_sub_f32_e32 v137, v188, v232
	s_waitcnt lgkmcnt(0)
; #define LAS __attribute__((address_space(3)))
; __device__ __forceinline__ unsigned cvt_pk_bf16(float lo, float hi) { const f32x2_t v = {lo, hi}; const bf16x2_t b = __builtin_convertvector(v, bf16x2_t); return __builtin_bit_cast(unsigned, b); }
; __device__ __forceinline__ float fexp2(float x) { return __builtin_amdgcn_exp2f(x); }
; __device__ __forceinline__ f32x4 mfma16(bf16x8 a, bf16x8 b, f32x4 c) { return __builtin_amdgcn_mfma_f32_16x16x32_bf16(a, b, c, 0, 0, 0); }
; template <bool FOX> ...
;     ...
;         const float alpha = fexp2(m_run[g] - m_new);
;         float ls = 0.f;
; #pragma unroll
;         for (int mt = 0; mt < 4; ++mt)
; #pragma unroll
;             for (int e = 0; e < 4; ++e) { const float p = fexp2(s[g][mt][e] - m_new); s[g][mt][e] = p; ls += p; }
;         l_run[g] = l_run[g] * alpha + ls; m_run[g] = m_new;
; #pragma unroll
;         for (int i = 0; i < 8; ++i) o[g][i] *= alpha;
; #pragma unroll
;         for (int i = 0; i < 2; ++i) pf[g][i] = mk8(cvt_pk_bf16(s[g][2 * i][0], s[g][2 * i][1]), cvt_pk_bf16(s[g][2 * i][2], s[g][2 * i][3]), cvt_pk_bf16(s[g][2 * i + 1][0], s[g][2 * i + 1][1]), cvt_pk_bf16(s[g][2 * i + 1][2], s[g][2 * i + 1][3]));
;     }
; #pragma unroll
;     for (int dt = 0; dt < 8; ++dt)
; #pragma unroll
;         for (int i = 0; i < 2; ++i) {
;             const u32x2 lo = *(const LAS u32x2*)(Vt + (dt * 16 + fr) * 72 + i * 32 + fq * 4), hi2 = *(const LAS u32x2*)(Vt + (dt * 16 + fr) * 72 + i * 32 + 16 + fq * 4);
;             const bf16x8 vf = mk8(lo.x, lo.y, hi2.x, hi2.y);
;             o[0][dt] = mfma16(vf, pf[0][i], o[0][dt]); o[1][dt] = mfma16(vf, pf[1][i], o[1][dt]);
;         }
	v_max3_f32 v233, v198, v156, v158
	v_exp_f32_e32 v157, v137
	v_sub_f32_e32 v137, v189, v232
	v_sub_f32_e32 v156, v184, v233
	v_exp_f32_e32 v159, v137
	v_sub_f32_e32 v137, v186, v232
	v_exp_f32_e32 v156, v156
	v_sub_f32_e32 v158, v185, v233
	v_exp_f32_e32 v189, v137
	v_sub_f32_e32 v137, v187, v232
	v_exp_f32_e32 v158, v158
	v_sub_f32_e32 v167, v182, v233
	v_exp_f32_e32 v187, v137
	v_sub_f32_e32 v137, v190, v232
	v_exp_f32_e32 v188, v167
	v_sub_f32_e32 v167, v183, v233
	v_sub_f32_e32 v152, v152, v233
	v_sub_f32_e32 v136, v199, v232
	v_exp_f32_e32 v199, v137
	v_sub_f32_e32 v137, v191, v232
	v_exp_f32_e32 v186, v167
	v_sub_f32_e32 v154, v154, v233
	v_exp_f32_e32 v200, v152
	v_sub_f32_e32 v152, v153, v233
	v_exp_f32_e32 v191, v137
	v_sub_f32_e32 v137, v192, v232
	v_sub_f32_e32 v166, v198, v233
	v_exp_f32_e32 v198, v154
	v_sub_f32_e32 v154, v155, v233
	v_exp_f32_e32 v192, v152
	v_pk_add_f32 v[152:153], v[156:157], 0 op_sel_hi:[1,0]
	v_exp_f32_e32 v190, v154
	v_pk_add_f32 v[152:153], v[158:159], v[152:153]
	v_exp_f32_e32 v201, v137
	v_sub_f32_e32 v137, v193, v232
	v_pk_add_f32 v[152:153], v[188:189], v[152:153]
	v_exp_f32_e32 v193, v137
	v_sub_f32_e32 v137, v196, v232
	v_sub_f32_e32 v146, v146, v233
	v_pk_add_f32 v[152:153], v[186:187], v[152:153]
	v_exp_f32_e32 v203, v137
	v_sub_f32_e32 v137, v197, v232
	v_exp_f32_e32 v202, v146
	v_pk_add_f32 v[152:153], v[198:199], v[152:153]
	v_sub_f32_e32 v146, v147, v233
	v_exp_f32_e32 v197, v137
	v_pk_add_f32 v[152:153], v[190:191], v[152:153]
	v_exp_f32_e32 v196, v146
	v_pk_add_f32 v[152:153], v[200:201], v[152:153]
	v_sub_f32_e32 v144, v144, v233
	v_pk_add_f32 v[152:153], v[192:193], v[152:153]
	v_exp_f32_e32 v204, v144
	v_sub_f32_e32 v144, v145, v233
	v_sub_f32_e32 v137, v194, v232
	v_pk_add_f32 v[152:153], v[202:203], v[152:153]
	v_exp_f32_e32 v194, v144
	v_sub_f32_e32 v144, v148, v233
	v_cvt_pk_bf16_f32 v148, v156, v158
	v_add_u32_e32 v156, 0x4000, v222
	v_pk_add_f32 v[146:147], v[196:197], v[152:153]
	ds_read2_b64 v[234:237], v156 offset0:128 offset1:132
	ds_read2_b64 v[246:249], v156 offset0:136 offset1:140
	v_add_u32_e32 v245, 0x4000, v223
	ds_read2_b64 v[250:253], v245 offset0:128 offset1:132
	v_add_u32_e32 v245, 0x4000, v223
	ds_read2_b64 v[152:155], v245 offset0:136 offset1:140
	v_exp_f32_e32 v206, v144
	v_sub_f32_e32 v144, v149, v233
	v_exp_f32_e32 v208, v144
	v_sub_f32_e32 v144, v150, v233
	v_exp_f32_e32 v160, v136
	v_exp_f32_e32 v210, v144
	v_sub_f32_e32 v144, v151, v233
	v_exp_f32_e32 v205, v137
	v_sub_f32_e32 v137, v195, v232
	v_exp_f32_e32 v212, v144
	v_exp_f32_e32 v144, v166
	v_exp_f32_e32 v195, v137
	v_sub_f32_e32 v137, v140, v232
	v_exp_f32_e32 v207, v137
	v_sub_f32_e32 v137, v141, v232
	v_exp_f32_e32 v209, v137
	v_sub_f32_e32 v137, v142, v232
	v_mov_b32_e32 v145, v160
	v_exp_f32_e32 v211, v137
	v_sub_f32_e32 v137, v143, v232
	v_pk_mul_f32 v[102:103], v[102:103], v[160:161] op_sel_hi:[1,0]
	v_pk_mul_f32 v[100:101], v[100:101], v[160:161] op_sel_hi:[1,0]
	v_cvt_pk_bf16_f32 v140, v157, v159
	v_cvt_pk_bf16_f32 v141, v189, v187
	v_cvt_pk_bf16_f32 v142, v199, v191
	v_cvt_pk_bf16_f32 v143, v201, v193
	v_pk_mul_f32 v[74:75], v[74:75], v[144:145] op_sel_hi:[1,0]
	v_pk_mul_f32 v[72:73], v[72:73], v[144:145] op_sel_hi:[1,0]
	v_cvt_pk_bf16_f32 v149, v188, v186
	v_cvt_pk_bf16_f32 v150, v198, v190
	v_cvt_pk_bf16_f32 v151, v200, v192
	s_waitcnt lgkmcnt(3)
	v_mfma_f32_16x16x32_bf16 v[100:103], v[234:237], v[140:143], v[100:103]
	v_add_f32_e64 v146, v204, v146
	v_add_f32_e64 v147, v205, v147
	v_exp_f32_e32 v213, v137
	v_pk_add_f32 v[146:147], v[194:195], v[146:147]
	v_mfma_f32_16x16x32_bf16 v[72:75], v[234:237], v[148:151], v[72:75]
	v_add_u32_e32 v245, 0x4000, v224
	ds_read2_b64 v[234:237], v245 offset0:128 offset1:132
	v_pk_add_f32 v[146:147], v[206:207], v[146:147]
	v_pk_mul_f32 v[138:139], v[134:135], v[160:161] op_sel_hi:[1,0]
	v_pk_add_f32 v[146:147], v[208:209], v[146:147]
	v_pk_mul_f32 v[136:137], v[132:133], v[160:161] op_sel_hi:[1,0]
	v_pk_add_f32 v[146:147], v[210:211], v[146:147]
	v_cvt_pk_bf16_f32 v132, v203, v197
	v_pk_add_f32 v[146:147], v[212:213], v[146:147]
	v_cvt_pk_bf16_f32 v133, v205, v195
	v_cvt_pk_bf16_f32 v134, v207, v209
	v_cvt_pk_bf16_f32 v135, v211, v213
	v_pk_fma_f32 v[180:181], v[180:181], v[144:145], v[146:147]
	v_pk_mul_f32 v[78:79], v[78:79], v[144:145] op_sel_hi:[1,0]
	v_pk_mul_f32 v[76:77], v[76:77], v[144:145] op_sel_hi:[1,0]
	v_pk_mul_f32 v[82:83], v[82:83], v[144:145] op_sel_hi:[1,0]
	v_pk_mul_f32 v[80:81], v[80:81], v[144:145] op_sel_hi:[1,0]
	v_pk_mul_f32 v[86:87], v[86:87], v[144:145] op_sel_hi:[1,0]
	v_pk_mul_f32 v[84:85], v[84:85], v[144:145] op_sel_hi:[1,0]
	v_pk_mul_f32 v[90:91], v[90:91], v[144:145] op_sel_hi:[1,0]
	v_pk_mul_f32 v[88:89], v[88:89], v[144:145] op_sel_hi:[1,0]
	v_pk_mul_f32 v[94:95], v[94:95], v[144:145] op_sel_hi:[1,0]
	v_pk_mul_f32 v[92:93], v[92:93], v[144:145] op_sel_hi:[1,0]
	v_pk_mul_f32 v[98:99], v[98:99], v[144:145] op_sel_hi:[1,0]
	v_pk_mul_f32 v[96:97], v[96:97], v[144:145] op_sel_hi:[1,0]
	v_pk_mul_f32 v[146:147], v[106:107], v[144:145] op_sel_hi:[1,0]
	v_pk_mul_f32 v[144:145], v[104:105], v[144:145] op_sel_hi:[1,0]
	v_cvt_pk_bf16_f32 v104, v202, v196
	v_cvt_pk_bf16_f32 v105, v204, v194
	v_cvt_pk_bf16_f32 v106, v206, v208
	v_cvt_pk_bf16_f32 v107, v210, v212
	v_add_u32_e32 v156, 0x4000, v223
	s_waitcnt lgkmcnt(3)
; #define LAS __attribute__((address_space(3)))
; __device__ __forceinline__ f32x4 mfma16(bf16x8 a, bf16x8 b, f32x4 c) { return __builtin_amdgcn_mfma_f32_16x16x32_bf16(a, b, c, 0, 0, 0); }
; template <bool FOX> ...
;     ...
; #pragma unroll
;     for (int dt = 0; dt < 8; ++dt)
; #pragma unroll
;         for (int i = 0; i < 2; ++i) {
;             const u32x2 lo = *(const LAS u32x2*)(Vt + (dt * 16 + fr) * 72 + i * 32 + fq * 4), hi2 = *(const LAS u32x2*)(Vt + (dt * 16 + fr) * 72 + i * 32 + 16 + fq * 4);
;             const bf16x8 vf = mk8(lo.x, lo.y, hi2.x, hi2.y);
;             o[0][dt] = mfma16(vf, pf[0][i], o[0][dt]); o[1][dt] = mfma16(vf, pf[1][i], o[1][dt]);
;         }
	v_mfma_f32_16x16x32_bf16 v[100:103], v[246:249], v[132:135], v[100:103]
	v_mul_f32_e64 v110, v110, v160
	v_mul_f32_e64 v111, v111, v160
	v_pk_mul_f32 v[108:109], v[108:109], v[160:161] op_sel_hi:[1,0]
	v_pk_mul_f32 v[114:115], v[114:115], v[160:161] op_sel_hi:[1,0]
	v_mfma_f32_16x16x32_bf16 v[72:75], v[246:249], v[104:107], v[72:75]
	v_add_u32_e32 v245, 0x4000, v224
	ds_read2_b64 v[246:249], v245 offset0:136 offset1:140
	v_pk_mul_f32 v[112:113], v[112:113], v[160:161] op_sel_hi:[1,0]
	v_pk_mul_f32 v[118:119], v[118:119], v[160:161] op_sel_hi:[1,0]
	s_waitcnt lgkmcnt(3)
	v_mfma_f32_16x16x32_bf16 v[108:111], v[250:253], v[140:143], v[108:111]
	v_mul_f32_e64 v116, v116, v160
	v_mul_f32_e64 v117, v117, v160
	v_pk_mul_f32 v[122:123], v[122:123], v[160:161] op_sel_hi:[1,0]
	v_pk_mul_f32 v[120:121], v[120:121], v[160:161] op_sel_hi:[1,0]
	v_mfma_f32_16x16x32_bf16 v[76:79], v[250:253], v[148:151], v[76:79]
	v_add_u32_e32 v245, 0x4000, v225
	ds_read2_b64 v[250:253], v245 offset0:128 offset1:132
	v_add_u32_e32 v156, 0x4000, v224
	v_pk_mul_f32 v[126:127], v[126:127], v[160:161] op_sel_hi:[1,0]
	s_waitcnt lgkmcnt(3)
	v_mfma_f32_16x16x32_bf16 v[108:111], v[152:155], v[132:135], v[108:111]
	v_mul_f32_e64 v124, v124, v160
	v_mul_f32_e64 v125, v125, v160
	v_pk_mul_f32 v[130:131], v[130:131], v[160:161] op_sel_hi:[1,0]
	v_pk_mul_f32 v[128:129], v[128:129], v[160:161] op_sel_hi:[1,0]
	v_mfma_f32_16x16x32_bf16 v[76:79], v[152:155], v[104:107], v[76:79]
	v_add_u32_e32 v245, 0x4000, v225
	ds_read2_b64 v[152:155], v245 offset0:136 offset1:140
	v_mov_b32_e32 v199, v232
	v_mov_b32_e32 v198, v233
	s_waitcnt lgkmcnt(3)
	v_mfma_f32_16x16x32_bf16 v[112:115], v[234:237], v[140:143], v[112:115]
	v_mfma_f32_16x16x32_bf16 v[80:83], v[234:237], v[148:151], v[80:83]
	v_add_u32_e32 v245, 0x6800, v222
	ds_read2_b64 v[234:237], v245 offset1:4
	v_add_u32_e32 v156, 0x4000, v225
	s_waitcnt lgkmcnt(3)
	v_mfma_f32_16x16x32_bf16 v[112:115], v[246:249], v[132:135], v[112:115]
	v_mfma_f32_16x16x32_bf16 v[80:83], v[246:249], v[104:107], v[80:83]
	v_add_u32_e32 v245, 0x6800, v222
	ds_read2_b64 v[246:249], v245 offset0:8 offset1:12
	s_waitcnt lgkmcnt(3)
	v_mfma_f32_16x16x32_bf16 v[116:119], v[250:253], v[140:143], v[116:119]
	v_mfma_f32_16x16x32_bf16 v[84:87], v[250:253], v[148:151], v[84:87]
	v_add_u32_e32 v245, 0x7000, v222
	ds_read2_b64 v[250:253], v245 offset0:32 offset1:36
	v_add_u32_e32 v156, 0x6800, v222
	s_waitcnt lgkmcnt(3)
	v_mfma_f32_16x16x32_bf16 v[116:119], v[152:155], v[132:135], v[116:119]
	v_mfma_f32_16x16x32_bf16 v[84:87], v[152:155], v[104:107], v[84:87]
	v_add_u32_e32 v245, 0x7000, v222
	ds_read2_b64 v[152:155], v245 offset0:40 offset1:44
	s_waitcnt lgkmcnt(3)
	v_mfma_f32_16x16x32_bf16 v[120:123], v[234:237], v[140:143], v[120:123]
	v_mfma_f32_16x16x32_bf16 v[88:91], v[234:237], v[148:151], v[88:91]
	v_add_u32_e32 v245, 0x7800, v222
	ds_read2_b64 v[234:237], v245 offset0:64 offset1:68
	v_add_u32_e32 v156, 0x7000, v222
	s_waitcnt lgkmcnt(3)
	v_mfma_f32_16x16x32_bf16 v[120:123], v[246:249], v[132:135], v[120:123]
	v_mfma_f32_16x16x32_bf16 v[88:91], v[246:249], v[104:107], v[88:91]
	v_add_u32_e32 v245, 0x7800, v222
	ds_read2_b64 v[246:249], v245 offset0:72 offset1:76
	s_waitcnt lgkmcnt(3)
	v_mfma_f32_16x16x32_bf16 v[124:127], v[250:253], v[140:143], v[124:127]
	v_mfma_f32_16x16x32_bf16 v[92:95], v[250:253], v[148:151], v[92:95]
	v_add_u32_e32 v245, 0x8000, v222
	ds_read2_b64 v[250:253], v245 offset0:96 offset1:100
	v_add_u32_e32 v156, 0x7800, v222
	s_waitcnt lgkmcnt(3)
	v_mfma_f32_16x16x32_bf16 v[124:127], v[152:155], v[132:135], v[124:127]
	v_mfma_f32_16x16x32_bf16 v[92:95], v[152:155], v[104:107], v[92:95]
	v_add_u32_e32 v245, 0x8000, v222
	ds_read2_b64 v[152:155], v245 offset0:104 offset1:108
	s_waitcnt lgkmcnt(3)
	v_mfma_f32_16x16x32_bf16 v[128:131], v[234:237], v[140:143], v[128:131]
	v_mfma_f32_16x16x32_bf16 v[96:99], v[234:237], v[148:151], v[96:99]
	v_add_u32_e32 v156, 0x8000, v222
	s_waitcnt lgkmcnt(2)
	v_mfma_f32_16x16x32_bf16 v[128:131], v[246:249], v[132:135], v[128:131]
	v_mfma_f32_16x16x32_bf16 v[96:99], v[246:249], v[104:107], v[96:99]
	s_waitcnt lgkmcnt(1)
	v_mfma_f32_16x16x32_bf16 v[136:139], v[250:253], v[140:143], v[136:139]
	v_mfma_f32_16x16x32_bf16 v[140:143], v[250:253], v[148:151], v[144:147]
	s_nop 2
	s_waitcnt lgkmcnt(0)
	v_mfma_f32_16x16x32_bf16 v[132:135], v[152:155], v[132:135], v[136:139]
	v_mfma_f32_16x16x32_bf16 v[104:107], v[152:155], v[104:107], v[140:143]

; #define LAS __attribute__((address_space(3)))
; __device__ __forceinline__ f32x4 mfma16(bf16x8 a, bf16x8 b, f32x4 c) { return __builtin_amdgcn_mfma_f32_16x16x32_bf16(a, b, c, 0, 0, 0); }
; template <bool FOX> ...
;     f32x4 s[2][4];
; #pragma unroll
;     for (int mt = 0; mt < 4; ++mt) {
;         s[0][mt] = (f32x4){0.f, 0.f, 0.f, 0.f}; s[1][mt] = (f32x4){0.f, 0.f, 0.f, 0.f};
; #pragma unroll
;         for (int ks = 0; ks < 4; ++ks) { const bf16x8 kf = *(const LAS bf16x8*)(Ks + (mt * 16 + fr) * 136 + ks * 32 + fq * 8); s[0][mt] = mfma16(kf, qf[0][ks], s[0][mt]); s[1][mt] = mfma16(kf, qf[1][ks], s[1][mt]); }
;     }
;     if (FOX) {
; #pragma unroll
;         for (int mt = 0; mt < 4; ++mt) { const f32x4 ck = *(const LAS f32x4*)(cum + j * 64 + mt * 16 + fq * 4);
; #pragma unroll
;             for (int e = 0; e < 4; ++e) { s[0][mt][e] += cq[0] - ck[e]; s[1][mt][e] += cq[1] - ck[e]; } }
.LBB0_278:
	ds_read_b128 v[234:237], v228 offset:35840
	ds_read_b128 v[246:249], v228 offset:35904
	ds_read_b128 v[250:253], v228 offset:35968
	ds_read_b128 v[186:189], v228 offset:36032
	ds_read_b128 v[194:197], v227 offset:256
	ds_read_b128 v[200:203], v227 offset:384
	s_add_i32 s4, s42, 1
	s_cmp_lt_u32 s4, s28
	s_waitcnt lgkmcnt(5)
	v_mfma_f32_16x16x32_bf16 v[140:143], v[234:237], v[0:3], 0
	s_waitcnt lgkmcnt(1)
	v_sub_f32_e32 v167, v35, v197
	v_sub_f32_e32 v166, v68, v196
	v_mfma_f32_16x16x32_bf16 v[136:139], v[234:237], v[16:19], 0
	ds_read_b128 v[234:237], v228 offset:40192
	v_mfma_f32_16x16x32_bf16 v[140:143], v[246:249], v[4:7], v[140:143]
	v_mfma_f32_16x16x32_bf16 v[136:139], v[246:249], v[20:23], v[136:139]
	ds_read_b128 v[246:249], v228 offset:40256
	s_waitcnt lgkmcnt(2)
	v_mfma_f32_16x16x32_bf16 v[140:143], v[250:253], v[8:11], v[140:143]
	v_mfma_f32_16x16x32_bf16 v[136:139], v[250:253], v[24:27], v[136:139]
	ds_read_b128 v[250:253], v228 offset:40320
	v_mfma_f32_16x16x32_bf16 v[190:193], v[186:189], v[28:31], v[136:139]
	s_nop 4
	v_mfma_f32_16x16x32_bf16 v[182:185], v[186:189], v[12:15], v[140:143]
	ds_read_b128 v[186:189], v228 offset:40384
	s_waitcnt lgkmcnt(3)
	v_mfma_f32_16x16x32_bf16 v[140:143], v[234:237], v[0:3], 0
	v_mfma_f32_16x16x32_bf16 v[136:139], v[234:237], v[16:19], 0
	ds_read_b128 v[234:237], v228 offset:44544
	s_waitcnt lgkmcnt(3)
	v_mfma_f32_16x16x32_bf16 v[140:143], v[246:249], v[4:7], v[140:143]
	v_mfma_f32_16x16x32_bf16 v[136:139], v[246:249], v[20:23], v[136:139]
	ds_read_b128 v[246:249], v228 offset:44608
	s_waitcnt lgkmcnt(3)
	v_mfma_f32_16x16x32_bf16 v[140:143], v[250:253], v[8:11], v[140:143]
	v_mfma_f32_16x16x32_bf16 v[136:139], v[250:253], v[24:27], v[136:139]
	ds_read_b128 v[250:253], v228 offset:44672
	s_waitcnt lgkmcnt(3)
	v_mfma_f32_16x16x32_bf16 v[152:155], v[186:189], v[12:15], v[140:143]
	v_mfma_f32_16x16x32_bf16 v[144:147], v[186:189], v[28:31], v[136:139]
	ds_read_b128 v[186:189], v228 offset:44736
	s_nop 3
	s_waitcnt lgkmcnt(3)
	v_mfma_f32_16x16x32_bf16 v[140:143], v[234:237], v[0:3], 0
	v_mfma_f32_16x16x32_bf16 v[136:139], v[234:237], v[16:19], 0
	ds_read_b128 v[234:237], v228 offset:48896
	s_waitcnt lgkmcnt(3)
	v_mfma_f32_16x16x32_bf16 v[140:143], v[246:249], v[4:7], v[140:143]
	v_mfma_f32_16x16x32_bf16 v[136:139], v[246:249], v[20:23], v[136:139]
	ds_read_b128 v[246:249], v228 offset:48960
	s_waitcnt lgkmcnt(3)
	v_mfma_f32_16x16x32_bf16 v[140:143], v[250:253], v[8:11], v[140:143]
	v_mfma_f32_16x16x32_bf16 v[136:139], v[250:253], v[24:27], v[136:139]
	ds_read_b128 v[250:253], v228 offset:49024
	s_waitcnt lgkmcnt(3)
	v_mfma_f32_16x16x32_bf16 v[156:159], v[186:189], v[12:15], v[140:143]
	v_mfma_f32_16x16x32_bf16 v[148:151], v[186:189], v[28:31], v[136:139]
	ds_read_b128 v[186:189], v228 offset:49088
	s_nop 3
	s_waitcnt lgkmcnt(3)
	v_mfma_f32_16x16x32_bf16 v[140:143], v[234:237], v[0:3], 0
	v_mfma_f32_16x16x32_bf16 v[136:139], v[234:237], v[16:19], 0
	s_waitcnt lgkmcnt(2)
	v_mfma_f32_16x16x32_bf16 v[140:143], v[246:249], v[4:7], v[140:143]
	v_mfma_f32_16x16x32_bf16 v[136:139], v[246:249], v[20:23], v[136:139]
	s_waitcnt lgkmcnt(1)
	v_mfma_f32_16x16x32_bf16 v[140:143], v[250:253], v[8:11], v[140:143]
	v_mfma_f32_16x16x32_bf16 v[136:139], v[250:253], v[24:27], v[136:139]
	s_waitcnt lgkmcnt(0)
	v_mfma_f32_16x16x32_bf16 v[140:143], v[186:189], v[12:15], v[140:143]
	v_mfma_f32_16x16x32_bf16 v[136:139], v[186:189], v[28:31], v[136:139]
	v_sub_f32_e32 v187, v33, v195
	v_sub_f32_e32 v186, v32, v194
	v_pk_add_f32 v[188:189], v[182:183], v[186:187]
	v_pk_add_f32 v[186:187], v[184:185], v[166:167]
	v_sub_f32_e32 v167, v71, v197
	v_sub_f32_e32 v166, v70, v196
	v_sub_f32_e32 v183, v69, v195
	v_sub_f32_e32 v182, v34, v194
	ds_read_b128 v[194:197], v227 offset:320
	v_pk_add_f32 v[184:185], v[190:191], v[182:183]
	v_pk_add_f32 v[182:183], v[192:193], v[166:167]
	s_waitcnt lgkmcnt(0)
	v_sub_f32_e32 v167, v35, v197
	v_sub_f32_e32 v166, v68, v196
	v_sub_f32_e32 v191, v33, v195
	v_sub_f32_e32 v190, v32, v194
	v_pk_add_f32 v[190:191], v[152:153], v[190:191]
	v_pk_add_f32 v[192:193], v[154:155], v[166:167]
	v_sub_f32_e32 v155, v71, v197
	v_sub_f32_e32 v154, v70, v196
	v_sub_f32_e32 v153, v69, v195
	v_sub_f32_e32 v152, v34, v194
	v_pk_add_f32 v[152:153], v[144:145], v[152:153]
	v_pk_add_f32 v[144:145], v[146:147], v[154:155]
	v_sub_f32_e32 v147, v35, v203
	v_sub_f32_e32 v146, v68, v202
	v_sub_f32_e32 v155, v33, v201
	v_sub_f32_e32 v154, v32, v200
	v_pk_add_f32 v[194:195], v[156:157], v[154:155]
	v_pk_add_f32 v[156:157], v[158:159], v[146:147]
	v_sub_f32_e32 v147, v71, v203
	v_sub_f32_e32 v146, v70, v202
	v_sub_f32_e32 v155, v69, v201
	v_sub_f32_e32 v154, v34, v200
	ds_read_b128 v[200:203], v227 offset:448
	v_pk_add_f32 v[148:149], v[148:149], v[154:155]
	v_pk_add_f32 v[146:147], v[150:151], v[146:147]
	s_waitcnt lgkmcnt(0)
	v_sub_f32_e32 v151, v35, v203
	v_sub_f32_e32 v150, v68, v202
	v_sub_f32_e32 v155, v33, v201
	v_sub_f32_e32 v154, v32, v200
	v_pk_add_f32 v[140:141], v[140:141], v[154:155]
	v_pk_add_f32 v[142:143], v[142:143], v[150:151]
	v_sub_f32_e32 v155, v71, v203
	v_sub_f32_e32 v154, v70, v202
	v_sub_f32_e32 v151, v69, v201
	v_sub_f32_e32 v150, v34, v200
	v_pk_add_f32 v[150:151], v[136:137], v[150:151]
	v_pk_add_f32 v[154:155], v[138:139], v[154:155]
	s_cbranch_scc1 .LBB0_280
; __device__ __forceinline__ float fexp2(float x) { return __builtin_amdgcn_exp2f(x); }
; template <bool FOX> ...
;     ...
;         if (diag) {
; #pragma unroll
;             for (int g = 0; g < 2; ++g)
; #pragma unroll
;                 for (int mt = 0; mt < 4; ++mt)
; #pragma unroll
;                     for (int e = 0; e < 4; ++e) if (j * 64 + mt * 16 + fq * 4 + e > qpos[g]) s[g][mt][e] = -INFINITY;
;         }
;     }
;     bf16x8 pf[2][2];
; #pragma unroll
;     for (int g = 0; g < 2; ++g) {
;         float mx = -INFINITY;
; #pragma unroll
;         for (int mt = 0; mt < 4; ++mt)
; #pragma unroll
;             for (int e = 0; e < 4; ++e) mx = fmaxf(mx, s[g][mt][e]);
;         mx = fmaxf(mx, __shfl_xor(mx, 16)); mx = fmaxf(mx, __shfl_xor(mx, 32));
;         const float m_new = fmaxf(m_run[g], mx);
;         const float alpha = fexp2(m_run[g] - m_new);
;         float ls = 0.f;
; #pragma unroll
;         for (int mt = 0; mt < 4; ++mt)
; #pragma unroll
;             for (int e = 0; e < 4; ++e) { const float p = fexp2(s[g][mt][e] - m_new); s[g][mt][e] = p; ls += p; }
;         l_run[g] = l_run[g] * alpha + ls; m_run[g] = m_new;
; #pragma unroll
;         for (int i = 0; i < 8; ++i) o[g][i] *= alpha;
	v_add_u32_e32 v137, s2, v221
	v_add_u32_e32 v138, 64, v137
	v_mov_b32_e32 v136, s33
	v_cmp_gt_i32_e32 vcc, v138, v175
	v_cmp_lt_i32_e64 s[4:5], v138, v175
	v_add_u32_e32 v139, 0x42, v137
	v_cndmask_b32_e32 v136, v188, v136, vcc
	v_cndmask_b32_e64 v188, v136, v188, s[4:5]
	v_cndmask_b32_e64 v189, v243, v189, s[4:5]
	v_cmp_le_i32_e64 s[4:5], v139, v175
	v_add_u32_e32 v158, 0x43, v137
	v_add_u32_e32 v159, 0x50, v137
	v_cndmask_b32_e64 v186, v243, v186, s[4:5]
	v_cmp_le_i32_e64 s[4:5], v158, v175
	v_mov_b32_e32 v136, s33
	v_add_u32_e32 v160, 0x52, v137
	v_cndmask_b32_e64 v187, v243, v187, s[4:5]
	v_cmp_gt_i32_e64 s[4:5], v159, v175
	v_add_u32_e32 v159, 0x51, v137
	v_add_u32_e32 v166, 0x53, v137
	v_cndmask_b32_e64 v190, v190, v136, s[4:5]
	v_cmp_le_i32_e64 s[4:5], v159, v175
	v_add_u32_e32 v167, 0x60, v137
	v_add_u32_e32 v196, 0x61, v137
	v_cndmask_b32_e64 v191, v243, v191, s[4:5]
	v_cmp_le_i32_e64 s[4:5], v160, v175
	v_add_u32_e32 v197, 0x62, v137
	v_add_u32_e32 v200, 0x63, v137
	v_cndmask_b32_e64 v192, v243, v192, s[4:5]
	v_cmp_le_i32_e64 s[4:5], v166, v175
	v_add_u32_e32 v201, 0x70, v137
	v_add_u32_e32 v202, 0x71, v137
	v_cndmask_b32_e64 v193, v243, v193, s[4:5]
	v_cmp_gt_i32_e64 s[4:5], v167, v175
	v_add_u32_e32 v203, 0x72, v137
	v_add_u32_e32 v137, 0x73, v137
	v_cndmask_b32_e64 v194, v194, v136, s[4:5]
	v_cmp_le_i32_e64 s[4:5], v196, v175
	s_nop 1
	v_cndmask_b32_e64 v195, v243, v195, s[4:5]
	v_cmp_le_i32_e64 s[4:5], v197, v175
	s_nop 1
	v_cndmask_b32_e64 v156, v243, v156, s[4:5]
	v_cmp_le_i32_e64 s[4:5], v200, v175
	s_nop 1
	v_cndmask_b32_e64 v157, v243, v157, s[4:5]
	v_cmp_gt_i32_e64 s[4:5], v201, v175
	s_nop 1
	v_cndmask_b32_e64 v140, v140, v136, s[4:5]
	v_cmp_le_i32_e64 s[4:5], v202, v175
	s_nop 1
	v_cndmask_b32_e64 v141, v243, v141, s[4:5]
	v_cmp_le_i32_e64 s[4:5], v203, v175
	s_nop 1
	v_cndmask_b32_e64 v142, v243, v142, s[4:5]
	v_cmp_le_i32_e64 s[4:5], v137, v175
	s_nop 1
	v_cndmask_b32_e64 v143, v243, v143, s[4:5]
	v_cmp_gt_i32_e64 s[4:5], v138, v179
	s_nop 1
	v_cndmask_b32_e64 v136, v184, v136, s[4:5]
	v_cmp_lt_i32_e64 s[4:5], v138, v179
	s_nop 1
	v_cndmask_b32_e64 v184, v136, v184, s[4:5]
	v_mov_b32_e32 v136, s33
	v_cndmask_b32_e32 v152, v152, v136, vcc
	v_cmp_le_i32_e32 vcc, v159, v179
	v_cndmask_b32_e64 v185, v243, v185, s[4:5]
	v_cmp_le_i32_e64 s[4:5], v139, v179
	v_cndmask_b32_e32 v153, v243, v153, vcc
	v_cmp_le_i32_e32 vcc, v160, v179
	v_cndmask_b32_e64 v182, v243, v182, s[4:5]
	v_cmp_le_i32_e64 s[4:5], v158, v179
	v_cndmask_b32_e32 v144, v243, v144, vcc
	v_cmp_le_i32_e32 vcc, v166, v179
	v_cndmask_b32_e64 v183, v243, v183, s[4:5]
	s_nop 0
	v_cndmask_b32_e32 v145, v243, v145, vcc
	v_cmp_gt_i32_e32 vcc, v167, v179
	s_nop 1
	v_cndmask_b32_e32 v148, v148, v136, vcc
	v_cmp_le_i32_e32 vcc, v196, v179
	s_nop 1
	v_cndmask_b32_e32 v149, v243, v149, vcc
	v_cmp_le_i32_e32 vcc, v197, v179
	s_nop 1
	v_cndmask_b32_e32 v146, v243, v146, vcc
	v_cmp_le_i32_e32 vcc, v200, v179
	s_nop 1
	v_cndmask_b32_e32 v147, v243, v147, vcc
	v_cmp_gt_i32_e32 vcc, v201, v179
	s_nop 1
	v_cndmask_b32_e32 v150, v150, v136, vcc
	v_cmp_le_i32_e32 vcc, v202, v179
	s_nop 1
	v_cndmask_b32_e32 v151, v243, v151, vcc
	v_cmp_le_i32_e32 vcc, v203, v179
	s_nop 1
	v_cndmask_b32_e32 v154, v243, v154, vcc
	v_cmp_le_i32_e32 vcc, v137, v179
	s_nop 1
	v_cndmask_b32_e32 v155, v243, v155, vcc
.LBB0_280:
	v_max3_f32 v136, v188, s33, v189
	v_max3_f32 v136, v136, v186, v187
	v_max3_f32 v136, v136, v190, v191
	v_max3_f32 v136, v136, v192, v193
	v_max3_f32 v136, v136, v194, v195
	v_max3_f32 v136, v136, v156, v157
	v_max3_f32 v136, v136, v140, v141
	v_max3_f32 v136, v136, v142, v143
	ds_bpermute_b32 v137, v216, v136
	s_waitcnt lgkmcnt(0)
	v_max_f32_e32 v137, v137, v137
	v_max_f32_e32 v136, v136, v137
	ds_bpermute_b32 v137, v215, v136
	s_waitcnt lgkmcnt(0)
	v_max3_f32 v229, v199, v136, v137
	v_sub_f32_e32 v137, v188, v229
	v_exp_f32_e32 v159, v137
	v_sub_f32_e32 v137, v189, v229
	v_exp_f32_e32 v189, v137
	v_sub_f32_e32 v137, v186, v229
	v_exp_f32_e32 v197, v137
	v_sub_f32_e32 v137, v187, v229
	v_exp_f32_e32 v187, v137
	v_sub_f32_e32 v137, v190, v229
	v_sub_f32_e32 v136, v199, v229
	v_exp_f32_e32 v199, v137
	v_sub_f32_e32 v137, v191, v229
	v_exp_f32_e32 v191, v137
	v_sub_f32_e32 v137, v192, v229
	v_exp_f32_e32 v201, v137
	v_sub_f32_e32 v137, v193, v229
	v_exp_f32_e32 v193, v137
	v_sub_f32_e32 v137, v194, v229
	v_exp_f32_e32 v203, v137
	v_sub_f32_e32 v137, v195, v229
	v_exp_f32_e32 v195, v137
	v_sub_f32_e32 v137, v156, v229
	v_max3_f32 v156, v184, s33, v185
	v_max3_f32 v156, v156, v182, v183
	v_max3_f32 v156, v156, v152, v153
	v_max3_f32 v156, v156, v144, v145
	v_max3_f32 v156, v156, v148, v149
	v_max3_f32 v156, v156, v146, v147
	v_max3_f32 v156, v156, v150, v151
	v_max3_f32 v156, v156, v154, v155
	ds_bpermute_b32 v158, v216, v156
	v_exp_f32_e32 v160, v136
	v_exp_f32_e32 v205, v137
	v_sub_f32_e32 v137, v157, v229
	v_exp_f32_e32 v157, v137
	s_waitcnt lgkmcnt(0)
	v_max_f32_e32 v158, v158, v158
	v_max_f32_e32 v156, v156, v158
	ds_bpermute_b32 v158, v215, v156
	v_sub_f32_e32 v137, v140, v229
	v_exp_f32_e32 v207, v137
	v_sub_f32_e32 v137, v141, v229
	v_exp_f32_e32 v209, v137
	s_waitcnt lgkmcnt(0)
; #define LAS __attribute__((address_space(3)))
; __device__ __forceinline__ unsigned cvt_pk_bf16(float lo, float hi) { const f32x2_t v = {lo, hi}; const bf16x2_t b = __builtin_convertvector(v, bf16x2_t); return __builtin_bit_cast(unsigned, b); }
; __device__ __forceinline__ float fexp2(float x) { return __builtin_amdgcn_exp2f(x); }
; __device__ __forceinline__ f32x4 mfma16(bf16x8 a, bf16x8 b, f32x4 c) { return __builtin_amdgcn_mfma_f32_16x16x32_bf16(a, b, c, 0, 0, 0); }
; template <bool FOX> ...
;     ...
;         const float alpha = fexp2(m_run[g] - m_new);
;         float ls = 0.f;
; #pragma unroll
;         for (int mt = 0; mt < 4; ++mt)
; #pragma unroll
;             for (int e = 0; e < 4; ++e) { const float p = fexp2(s[g][mt][e] - m_new); s[g][mt][e] = p; ls += p; }
;         l_run[g] = l_run[g] * alpha + ls; m_run[g] = m_new;
; #pragma unroll
;         for (int i = 0; i < 8; ++i) o[g][i] *= alpha;
; #pragma unroll
;         for (int i = 0; i < 2; ++i) pf[g][i] = mk8(cvt_pk_bf16(s[g][2 * i][0], s[g][2 * i][1]), cvt_pk_bf16(s[g][2 * i][2], s[g][2 * i][3]), cvt_pk_bf16(s[g][2 * i + 1][0], s[g][2 * i + 1][1]), cvt_pk_bf16(s[g][2 * i + 1][2], s[g][2 * i + 1][3]));
;     }
; #pragma unroll
;     for (int dt = 0; dt < 8; ++dt)
; #pragma unroll
;         for (int i = 0; i < 2; ++i) {
;             const u32x2 lo = *(const LAS u32x2*)(Vt + (dt * 16 + fr) * 72 + i * 32 + fq * 4), hi2 = *(const LAS u32x2*)(Vt + (dt * 16 + fr) * 72 + i * 32 + 16 + fq * 4);
;             const bf16x8 vf = mk8(lo.x, lo.y, hi2.x, hi2.y);
;             o[0][dt] = mfma16(vf, pf[0][i], o[0][dt]); o[1][dt] = mfma16(vf, pf[1][i], o[1][dt]);
;         }
	v_max3_f32 v230, v198, v156, v158
	v_sub_f32_e32 v156, v184, v230
	v_exp_f32_e32 v158, v156
	v_sub_f32_e32 v156, v185, v230
	v_exp_f32_e32 v188, v156
	v_sub_f32_e32 v156, v182, v230
	v_sub_f32_e32 v144, v144, v230
	v_exp_f32_e32 v196, v156
	v_sub_f32_e32 v156, v183, v230
	v_sub_f32_e32 v152, v152, v230
	v_exp_f32_e32 v200, v144
	v_sub_f32_e32 v144, v145, v230
	v_sub_f32_e32 v166, v198, v230
	v_exp_f32_e32 v186, v156
	v_exp_f32_e32 v198, v152
	v_sub_f32_e32 v152, v153, v230
	v_exp_f32_e32 v192, v144
	v_sub_f32_e32 v144, v148, v230
	v_exp_f32_e32 v190, v152
	v_pk_add_f32 v[152:153], v[158:159], 0 op_sel_hi:[1,0]
	v_exp_f32_e32 v202, v144
	v_sub_f32_e32 v144, v149, v230
	v_pk_add_f32 v[152:153], v[188:189], v[152:153]
	v_exp_f32_e32 v194, v144
	v_sub_f32_e32 v144, v146, v230
	v_pk_add_f32 v[152:153], v[196:197], v[152:153]
	v_exp_f32_e32 v204, v144
	v_sub_f32_e32 v144, v147, v230
	v_pk_add_f32 v[152:153], v[186:187], v[152:153]
	v_exp_f32_e32 v156, v144
	v_sub_f32_e32 v144, v150, v230
	v_pk_add_f32 v[152:153], v[198:199], v[152:153]
	v_exp_f32_e32 v206, v144
	v_sub_f32_e32 v144, v151, v230
	v_pk_add_f32 v[152:153], v[190:191], v[152:153]
	v_exp_f32_e32 v208, v144
	v_sub_f32_e32 v144, v154, v230
	v_exp_f32_e32 v210, v144
	v_sub_f32_e32 v144, v155, v230
	v_pk_add_f32 v[146:147], v[200:201], v[152:153]
	ds_read2_b64 v[234:237], v226 offset1:4
	ds_read2_b64 v[246:249], v226 offset0:8 offset1:12
	v_add_u32_e32 v245, 0xd000, v223
	ds_read2_b64 v[250:253], v245 offset1:4
	v_add_u32_e32 v245, 0xd000, v223
	ds_read2_b64 v[152:155], v245 offset0:8 offset1:12
	v_exp_f32_e32 v212, v144
	v_exp_f32_e32 v144, v166
	v_sub_f32_e32 v137, v142, v229
	v_mov_b32_e32 v145, v160
	v_exp_f32_e32 v211, v137
	v_sub_f32_e32 v137, v143, v229
	v_pk_mul_f32 v[102:103], v[102:103], v[160:161] op_sel_hi:[1,0]
	v_pk_mul_f32 v[100:101], v[100:101], v[160:161] op_sel_hi:[1,0]
	v_cvt_pk_bf16_f32 v140, v159, v189
	v_cvt_pk_bf16_f32 v141, v197, v187
	v_cvt_pk_bf16_f32 v142, v199, v191
	v_cvt_pk_bf16_f32 v143, v201, v193
	v_pk_add_f32 v[146:147], v[192:193], v[146:147]
	v_pk_mul_f32 v[74:75], v[74:75], v[144:145] op_sel_hi:[1,0]
	v_pk_mul_f32 v[72:73], v[72:73], v[144:145] op_sel_hi:[1,0]
	v_cvt_pk_bf16_f32 v148, v158, v188
	v_cvt_pk_bf16_f32 v149, v196, v186
	v_cvt_pk_bf16_f32 v150, v198, v190
	v_cvt_pk_bf16_f32 v151, v200, v192
	v_pk_add_f32 v[146:147], v[202:203], v[146:147]
	s_waitcnt lgkmcnt(3)
	v_mfma_f32_16x16x32_bf16 v[100:103], v[234:237], v[140:143], v[100:103]
	v_add_f32_e64 v146, v194, v146
	v_add_f32_e64 v147, v195, v147
	v_exp_f32_e32 v213, v137
	v_pk_add_f32 v[146:147], v[204:205], v[146:147]
	v_mfma_f32_16x16x32_bf16 v[72:75], v[234:237], v[148:151], v[72:75]
	v_add_u32_e32 v245, 0xd000, v224
	ds_read2_b64 v[234:237], v245 offset1:4
	v_pk_add_f32 v[146:147], v[156:157], v[146:147]
	v_pk_mul_f32 v[138:139], v[134:135], v[160:161] op_sel_hi:[1,0]
	v_pk_add_f32 v[146:147], v[206:207], v[146:147]
	v_pk_mul_f32 v[136:137], v[132:133], v[160:161] op_sel_hi:[1,0]
	v_pk_add_f32 v[146:147], v[208:209], v[146:147]
	v_cvt_pk_bf16_f32 v132, v203, v195
	v_pk_add_f32 v[146:147], v[210:211], v[146:147]
	v_cvt_pk_bf16_f32 v133, v205, v157
	v_pk_add_f32 v[146:147], v[212:213], v[146:147]
	v_cvt_pk_bf16_f32 v134, v207, v209
	v_cvt_pk_bf16_f32 v135, v211, v213
	v_pk_fma_f32 v[180:181], v[180:181], v[144:145], v[146:147]
	v_pk_mul_f32 v[78:79], v[78:79], v[144:145] op_sel_hi:[1,0]
	v_pk_mul_f32 v[76:77], v[76:77], v[144:145] op_sel_hi:[1,0]
	v_pk_mul_f32 v[82:83], v[82:83], v[144:145] op_sel_hi:[1,0]
	v_pk_mul_f32 v[80:81], v[80:81], v[144:145] op_sel_hi:[1,0]
	v_pk_mul_f32 v[86:87], v[86:87], v[144:145] op_sel_hi:[1,0]
	v_pk_mul_f32 v[84:85], v[84:85], v[144:145] op_sel_hi:[1,0]
	v_pk_mul_f32 v[90:91], v[90:91], v[144:145] op_sel_hi:[1,0]
	v_pk_mul_f32 v[88:89], v[88:89], v[144:145] op_sel_hi:[1,0]
	v_pk_mul_f32 v[94:95], v[94:95], v[144:145] op_sel_hi:[1,0]
	v_pk_mul_f32 v[92:93], v[92:93], v[144:145] op_sel_hi:[1,0]
	v_pk_mul_f32 v[98:99], v[98:99], v[144:145] op_sel_hi:[1,0]
	v_pk_mul_f32 v[96:97], v[96:97], v[144:145] op_sel_hi:[1,0]
	v_pk_mul_f32 v[146:147], v[106:107], v[144:145] op_sel_hi:[1,0]
	v_pk_mul_f32 v[144:145], v[104:105], v[144:145] op_sel_hi:[1,0]
	v_cvt_pk_bf16_f32 v104, v202, v194
	v_cvt_pk_bf16_f32 v105, v204, v156
	v_cvt_pk_bf16_f32 v106, v206, v208
	v_cvt_pk_bf16_f32 v107, v210, v212
	v_add_u32_e32 v156, 0xd000, v223
	s_waitcnt lgkmcnt(3)
; #define LAS __attribute__((address_space(3)))
; __device__ __forceinline__ unsigned cvt_pk_bf16(float lo, float hi) { const f32x2_t v = {lo, hi}; const bf16x2_t b = __builtin_convertvector(v, bf16x2_t); return __builtin_bit_cast(unsigned, b); }
; __device__ __forceinline__ f32x4 mfma16(bf16x8 a, bf16x8 b, f32x4 c) { return __builtin_amdgcn_mfma_f32_16x16x32_bf16(a, b, c, 0, 0, 0); }
; template <bool FOX> ...
;     ...
;         for (int i = 0; i < 8; ++i) o[g][i] *= alpha;
; #pragma unroll
;         for (int i = 0; i < 2; ++i) pf[g][i] = mk8(cvt_pk_bf16(s[g][2 * i][0], s[g][2 * i][1]), cvt_pk_bf16(s[g][2 * i][2], s[g][2 * i][3]), cvt_pk_bf16(s[g][2 * i + 1][0], s[g][2 * i + 1][1]), cvt_pk_bf16(s[g][2 * i + 1][2], s[g][2 * i + 1][3]));
;     }
; #pragma unroll
;     for (int dt = 0; dt < 8; ++dt)
; #pragma unroll
;         for (int i = 0; i < 2; ++i) {
;             const u32x2 lo = *(const LAS u32x2*)(Vt + (dt * 16 + fr) * 72 + i * 32 + fq * 4), hi2 = *(const LAS u32x2*)(Vt + (dt * 16 + fr) * 72 + i * 32 + 16 + fq * 4);
;             const bf16x8 vf = mk8(lo.x, lo.y, hi2.x, hi2.y);
;             o[0][dt] = mfma16(vf, pf[0][i], o[0][dt]); o[1][dt] = mfma16(vf, pf[1][i], o[1][dt]);
;         }
	v_mfma_f32_16x16x32_bf16 v[100:103], v[246:249], v[132:135], v[100:103]
	v_mul_f32_e64 v110, v110, v160
	v_mul_f32_e64 v111, v111, v160
	v_pk_mul_f32 v[108:109], v[108:109], v[160:161] op_sel_hi:[1,0]
	v_pk_mul_f32 v[114:115], v[114:115], v[160:161] op_sel_hi:[1,0]
	v_mfma_f32_16x16x32_bf16 v[72:75], v[246:249], v[104:107], v[72:75]
	v_add_u32_e32 v245, 0xd000, v224
	ds_read2_b64 v[246:249], v245 offset0:8 offset1:12
	v_pk_mul_f32 v[112:113], v[112:113], v[160:161] op_sel_hi:[1,0]
	v_pk_mul_f32 v[118:119], v[118:119], v[160:161] op_sel_hi:[1,0]
	s_waitcnt lgkmcnt(3)
	v_mfma_f32_16x16x32_bf16 v[108:111], v[250:253], v[140:143], v[108:111]
	v_mul_f32_e64 v116, v116, v160
	v_mul_f32_e64 v117, v117, v160
	v_pk_mul_f32 v[122:123], v[122:123], v[160:161] op_sel_hi:[1,0]
	v_pk_mul_f32 v[120:121], v[120:121], v[160:161] op_sel_hi:[1,0]
	v_mfma_f32_16x16x32_bf16 v[76:79], v[250:253], v[148:151], v[76:79]
	v_add_u32_e32 v245, 0xd000, v225
	ds_read2_b64 v[250:253], v245 offset1:4
	v_add_u32_e32 v156, 0xd000, v224
	v_pk_mul_f32 v[126:127], v[126:127], v[160:161] op_sel_hi:[1,0]
	s_waitcnt lgkmcnt(3)
	v_mfma_f32_16x16x32_bf16 v[108:111], v[152:155], v[132:135], v[108:111]
	v_mul_f32_e64 v124, v124, v160
	v_mul_f32_e64 v125, v125, v160
	v_pk_mul_f32 v[130:131], v[130:131], v[160:161] op_sel_hi:[1,0]
	v_pk_mul_f32 v[128:129], v[128:129], v[160:161] op_sel_hi:[1,0]
	v_mfma_f32_16x16x32_bf16 v[76:79], v[152:155], v[104:107], v[76:79]
	v_add_u32_e32 v245, 0xd000, v225
	ds_read2_b64 v[152:155], v245 offset0:8 offset1:12
	v_mov_b32_e32 v199, v229
	v_mov_b32_e32 v198, v230
	s_waitcnt lgkmcnt(3)
	v_mfma_f32_16x16x32_bf16 v[112:115], v[234:237], v[140:143], v[112:115]
	v_mfma_f32_16x16x32_bf16 v[80:83], v[234:237], v[148:151], v[80:83]
	v_add_u32_e32 v245, 0xf000, v222
	ds_read2_b64 v[234:237], v245 offset0:128 offset1:132
	v_add_u32_e32 v156, 0xd000, v225
	s_waitcnt lgkmcnt(3)
	v_mfma_f32_16x16x32_bf16 v[112:115], v[246:249], v[132:135], v[112:115]
	v_mfma_f32_16x16x32_bf16 v[80:83], v[246:249], v[104:107], v[80:83]
	v_add_u32_e32 v245, 0xf000, v222
	ds_read2_b64 v[246:249], v245 offset0:136 offset1:140
	s_waitcnt lgkmcnt(3)
	v_mfma_f32_16x16x32_bf16 v[116:119], v[250:253], v[140:143], v[116:119]
	v_mfma_f32_16x16x32_bf16 v[84:87], v[250:253], v[148:151], v[84:87]
	v_add_u32_e32 v245, 0xf800, v222
	ds_read2_b64 v[250:253], v245 offset0:160 offset1:164
	v_add_u32_e32 v156, 0xf000, v222
	s_waitcnt lgkmcnt(3)
	v_mfma_f32_16x16x32_bf16 v[116:119], v[152:155], v[132:135], v[116:119]
	v_mfma_f32_16x16x32_bf16 v[84:87], v[152:155], v[104:107], v[84:87]
	v_add_u32_e32 v245, 0xf800, v222
	ds_read2_b64 v[152:155], v245 offset0:168 offset1:172
	s_waitcnt lgkmcnt(3)
	v_mfma_f32_16x16x32_bf16 v[120:123], v[234:237], v[140:143], v[120:123]
	v_mfma_f32_16x16x32_bf16 v[88:91], v[234:237], v[148:151], v[88:91]
	v_add_u32_e32 v245, 0x3000, v226
	ds_read2_b64 v[234:237], v245 offset0:192 offset1:196
	v_add_u32_e32 v156, 0xf800, v222
	s_waitcnt lgkmcnt(3)
	v_mfma_f32_16x16x32_bf16 v[120:123], v[246:249], v[132:135], v[120:123]
	v_mfma_f32_16x16x32_bf16 v[88:91], v[246:249], v[104:107], v[88:91]
	v_add_u32_e32 v245, 0x3000, v226
	ds_read2_b64 v[246:249], v245 offset0:200 offset1:204
	s_waitcnt lgkmcnt(3)
	v_mfma_f32_16x16x32_bf16 v[124:127], v[250:253], v[140:143], v[124:127]
	v_mfma_f32_16x16x32_bf16 v[92:95], v[250:253], v[148:151], v[92:95]
	v_add_u32_e32 v245, 0x3800, v226
	ds_read2_b64 v[250:253], v245 offset0:224 offset1:228
	v_add_u32_e32 v156, 0x3000, v226
	s_waitcnt lgkmcnt(3)
	v_mfma_f32_16x16x32_bf16 v[124:127], v[152:155], v[132:135], v[124:127]
	v_mfma_f32_16x16x32_bf16 v[92:95], v[152:155], v[104:107], v[92:95]
	v_add_u32_e32 v245, 0x3800, v226
	ds_read2_b64 v[152:155], v245 offset0:232 offset1:236
	s_waitcnt lgkmcnt(3)
	v_mfma_f32_16x16x32_bf16 v[128:131], v[234:237], v[140:143], v[128:131]
	v_mfma_f32_16x16x32_bf16 v[96:99], v[234:237], v[148:151], v[96:99]
	v_add_u32_e32 v156, 0x3800, v226
	s_waitcnt lgkmcnt(2)
	v_mfma_f32_16x16x32_bf16 v[128:131], v[246:249], v[132:135], v[128:131]
	v_mfma_f32_16x16x32_bf16 v[96:99], v[246:249], v[104:107], v[96:99]
	s_waitcnt lgkmcnt(1)
	v_mfma_f32_16x16x32_bf16 v[136:139], v[250:253], v[140:143], v[136:139]
	v_mfma_f32_16x16x32_bf16 v[140:143], v[250:253], v[148:151], v[144:147]
	s_nop 2
	s_waitcnt lgkmcnt(0)
	v_mfma_f32_16x16x32_bf16 v[132:135], v[152:155], v[132:135], v[136:139]
	v_mfma_f32_16x16x32_bf16 v[104:107], v[152:155], v[104:107], v[140:143]
